# P4b transposed-copy tiles: all tiles of a workgroup loaded up front into separate register banks, then transposed one by one (one load latency per workgroup instead of one per tile)
# baseline (speedup 1.0000x reference)
; static __device__ __forceinline__ KP lp(KP q) { asm volatile("" : "+s"(q)); return q; }
; DI int tidx() { int t = __builtin_amdgcn_workitem_id_x(); asm volatile("" : "+v"(t)); return t; }
; DI void yc_transpose_unit(KP p, int u, char* smem) {
;   const int tid = tidx();
;   const u16* src; u16* dst; int rowlen;
;   int b, cb, tb;
;   if (u < 2048) { b = u >> 9; cb = (u >> 6) & 7; tb = u & 63; rowlen = 4096;
;     src = (const u16*)(p->ws + OFF_YCT) + (size_t)(b * 512 + cb * 64) * 4096 + tb * 64;
;     dst = (u16*)(p->ws + OFF_YC) + (size_t)(b * 4096 + tb * 64) * 512 + cb * 64; }
;   else { const int uu = u - 2048; b = uu >> 5; cb = (uu >> 2) & 7; tb = uu & 3; rowlen = 256;
;     src = (const u16*)(p->ws + OFF_YCT) + (size_t)NB * 512 * 4096 + (size_t)(b * 512 + cb * 64) * 256 + tb * 64;
;     dst = (u16*)(p->ws + OFF_YC) + (size_t)(MLAT + b * 256 + tb * 64) * 512 + cb * 64; }
;   u16* tile = (u16*)smem;
;   const int r = tid >> 2, q = tid & 3;
;   __syncthreads();
;   {
;     const u32x4 v0 = *(const u32x4*)(src + (size_t)r * rowlen + q * 16);
;     const u32x4 v1 = *(const u32x4*)(src + (size_t)r * rowlen + q * 16 + 8);
;     unsigned* tp = (unsigned*)(tile + r * 66 + q * 16);
;     tp[0] = v0.x; tp[1] = v0.y; tp[2] = v0.z; tp[3] = v0.w; tp[4] = v1.x; tp[5] = v1.y; tp[6] = v1.z; tp[7] = v1.w;
; __global__ void __launch_bounds__(256, 2) trunk_megakernel(Params pk) {
;     ...
;       for (int u = B; u < 2176 + (l ? 2048 : 2176); u += G) {
;         if (u < 2176) { if (l == 0 || ((u % 544) >> 3) >= 4) lru_unit(lp(p), l, u, 3, smem, rep + 1 < REP_L3); }
;         else yc_transpose_unit(lp(p), u - 2176, smem);
.LBB0_1156:
	s_cmpk_gt_i32 s26, 0x87f
	s_mov_b64 s[6:7], -1
	s_cbranch_scc0 .LBB0_1162
	s_load_dwordx2 s[4:5], s[0:1], 0x130
	v_lshrrev_b32_e32 v80, 2, v0
	v_and_b32_e32 v81, 3, v0
	v_mul_u32_u24_e32 v83, 0x840, v81
	v_lshlrev_b32_e32 v81, 5, v81
	v_mul_u32_u24_e32 v82, 0x84, v80
	v_lshl_add_u32 v83, v80, 1, v83
	v_add_u32_e32 v82, v82, v81
	v_lshlrev_b32_e32 v84, 10, v80
	v_add_u32_e32 v84, v84, v81
	s_mov_b32 s10, 0
	s_waitcnt lgkmcnt(0)
	s_mov_b32 s2, s26
	s_cmp_ge_i32 s2, s21
	s_cbranch_scc1 .Lyc_loaded
	s_add_i32 s2, s2, 0xfffff780
	s_cmpk_gt_u32 s2, 0x7ff
	s_cbranch_scc1 .Lyc_sc0
	s_lshr_b32 s3, s2, 6
	s_lshl_b32 s3, s3, 19
	s_and_b32 s13, s2, 63
	s_lshl_b32 s14, s13, 7
	s_add_u32 s3, s3, s14
	s_add_u32 s3, s3, 0x2200000
	s_movk_i32 s12, 0x2000
	s_branch .Lyc_sd0
.Lyc_sc0:
	s_add_i32 s13, s2, 0xfffff800
	s_lshr_b32 s3, s13, 2
	s_lshl_b32 s3, s3, 15
	s_and_b32 s13, s13, 3
	s_lshl_b32 s14, s13, 7
	s_add_u32 s3, s3, s14
	s_add_u32 s3, s3, 0x3200000
	s_movk_i32 s12, 0x200
.Lyc_sd0:
	s_add_u32 s8, s4, s3
	s_addc_u32 s9, s5, 0
	v_mul_u32_u24_e32 v85, s12, v80
	v_add_u32_e32 v85, v85, v81
	s_add_i32 s10, s10, 1
	global_load_dwordx4 v[40:43], v85, s[8:9]
	global_load_dwordx4 v[44:47], v85, s[8:9] offset:16
	s_mul_i32 s2, s61, 1
	s_add_i32 s2, s2, s26
	s_cmp_ge_i32 s2, s21
	s_cbranch_scc1 .Lyc_loaded
	s_add_i32 s2, s2, 0xfffff780
	s_cmpk_gt_u32 s2, 0x7ff
	s_cbranch_scc1 .Lyc_sc1
	s_lshr_b32 s3, s2, 6
	s_lshl_b32 s3, s3, 19
	s_and_b32 s13, s2, 63
	s_lshl_b32 s14, s13, 7
	s_add_u32 s3, s3, s14
	s_add_u32 s3, s3, 0x2200000
	s_movk_i32 s12, 0x2000
	s_branch .Lyc_sd1

; DI void yc_transpose_unit(KP p, int u, char* smem) {
;     ...
;   if (u < 2048) { b = u >> 9; cb = (u >> 6) & 7; tb = u & 63; rowlen = 4096;
;     src = (const u16*)(p->ws + OFF_YCT) + (size_t)(b * 512 + cb * 64) * 4096 + tb * 64;
;     dst = (u16*)(p->ws + OFF_YC) + (size_t)(b * 4096 + tb * 64) * 512 + cb * 64; }
;   else { const int uu = u - 2048; b = uu >> 5; cb = (uu >> 2) & 7; tb = uu & 3; rowlen = 256;
;     src = (const u16*)(p->ws + OFF_YCT) + (size_t)NB * 512 * 4096 + (size_t)(b * 512 + cb * 64) * 256 + tb * 64;
;     dst = (u16*)(p->ws + OFF_YC) + (size_t)(MLAT + b * 256 + tb * 64) * 512 + cb * 64; }
;   u16* tile = (u16*)smem;
;   const int r = tid >> 2, q = tid & 3;
;   __syncthreads();
;   {
;     const u32x4 v0 = *(const u32x4*)(src + (size_t)r * rowlen + q * 16);
;     const u32x4 v1 = *(const u32x4*)(src + (size_t)r * rowlen + q * 16 + 8);
.Lyc_sd1:
	s_add_u32 s8, s4, s3
	s_addc_u32 s9, s5, 0
	v_mul_u32_u24_e32 v85, s12, v80
	v_add_u32_e32 v85, v85, v81
	s_add_i32 s10, s10, 1
	global_load_dwordx4 v[48:51], v85, s[8:9]
	global_load_dwordx4 v[52:55], v85, s[8:9] offset:16
	s_mul_i32 s2, s61, 2
	s_add_i32 s2, s2, s26
	s_cmp_ge_i32 s2, s21
	s_cbranch_scc1 .Lyc_loaded
	s_add_i32 s2, s2, 0xfffff780
	s_cmpk_gt_u32 s2, 0x7ff
	s_cbranch_scc1 .Lyc_sc2
	s_lshr_b32 s3, s2, 6
	s_lshl_b32 s3, s3, 19
	s_and_b32 s13, s2, 63
	s_lshl_b32 s14, s13, 7
	s_add_u32 s3, s3, s14
	s_add_u32 s3, s3, 0x2200000
	s_movk_i32 s12, 0x2000
	s_branch .Lyc_sd2

; DI void yc_transpose_unit(KP p, int u, char* smem) {
;     ...
;   if (u < 2048) { b = u >> 9; cb = (u >> 6) & 7; tb = u & 63; rowlen = 4096;
;     src = (const u16*)(p->ws + OFF_YCT) + (size_t)(b * 512 + cb * 64) * 4096 + tb * 64;
;     dst = (u16*)(p->ws + OFF_YC) + (size_t)(b * 4096 + tb * 64) * 512 + cb * 64; }
;   else { const int uu = u - 2048; b = uu >> 5; cb = (uu >> 2) & 7; tb = uu & 3; rowlen = 256;
;     src = (const u16*)(p->ws + OFF_YCT) + (size_t)NB * 512 * 4096 + (size_t)(b * 512 + cb * 64) * 256 + tb * 64;
;     dst = (u16*)(p->ws + OFF_YC) + (size_t)(MLAT + b * 256 + tb * 64) * 512 + cb * 64; }
;   u16* tile = (u16*)smem;
;   const int r = tid >> 2, q = tid & 3;
;   __syncthreads();
;   {
;     const u32x4 v0 = *(const u32x4*)(src + (size_t)r * rowlen + q * 16);
;     const u32x4 v1 = *(const u32x4*)(src + (size_t)r * rowlen + q * 16 + 8);
.Lyc_sd2:
	s_add_u32 s8, s4, s3
	s_addc_u32 s9, s5, 0
	v_mul_u32_u24_e32 v85, s12, v80
	v_add_u32_e32 v85, v85, v81
	s_add_i32 s10, s10, 1
	global_load_dwordx4 v[56:59], v85, s[8:9]
	global_load_dwordx4 v[60:63], v85, s[8:9] offset:16
	s_mul_i32 s2, s61, 3
	s_add_i32 s2, s2, s26
	s_cmp_ge_i32 s2, s21
	s_cbranch_scc1 .Lyc_loaded
	s_add_i32 s2, s2, 0xfffff780
	s_cmpk_gt_u32 s2, 0x7ff
	s_cbranch_scc1 .Lyc_sc3
	s_lshr_b32 s3, s2, 6
	s_lshl_b32 s3, s3, 19
	s_and_b32 s13, s2, 63
	s_lshl_b32 s14, s13, 7
	s_add_u32 s3, s3, s14
	s_add_u32 s3, s3, 0x2200000
	s_movk_i32 s12, 0x2000
	s_branch .Lyc_sd3

; DI void yc_transpose_unit(KP p, int u, char* smem) {
;     ...
;   if (u < 2048) { b = u >> 9; cb = (u >> 6) & 7; tb = u & 63; rowlen = 4096;
;     src = (const u16*)(p->ws + OFF_YCT) + (size_t)(b * 512 + cb * 64) * 4096 + tb * 64;
;     dst = (u16*)(p->ws + OFF_YC) + (size_t)(b * 4096 + tb * 64) * 512 + cb * 64; }
;   else { const int uu = u - 2048; b = uu >> 5; cb = (uu >> 2) & 7; tb = uu & 3; rowlen = 256;
;     src = (const u16*)(p->ws + OFF_YCT) + (size_t)NB * 512 * 4096 + (size_t)(b * 512 + cb * 64) * 256 + tb * 64;
;     dst = (u16*)(p->ws + OFF_YC) + (size_t)(MLAT + b * 256 + tb * 64) * 512 + cb * 64; }
;   u16* tile = (u16*)smem;
;   const int r = tid >> 2, q = tid & 3;
;   __syncthreads();
;   {
;     const u32x4 v0 = *(const u32x4*)(src + (size_t)r * rowlen + q * 16);
;     const u32x4 v1 = *(const u32x4*)(src + (size_t)r * rowlen + q * 16 + 8);
.Lyc_sd3:
	s_add_u32 s8, s4, s3
	s_addc_u32 s9, s5, 0
	v_mul_u32_u24_e32 v85, s12, v80
	v_add_u32_e32 v85, v85, v81
	s_add_i32 s10, s10, 1
	global_load_dwordx4 v[64:67], v85, s[8:9]
	global_load_dwordx4 v[68:71], v85, s[8:9] offset:16
	s_mul_i32 s2, s61, 4
	s_add_i32 s2, s2, s26
	s_cmp_ge_i32 s2, s21
	s_cbranch_scc1 .Lyc_loaded
	s_add_i32 s2, s2, 0xfffff780
	s_cmpk_gt_u32 s2, 0x7ff
	s_cbranch_scc1 .Lyc_sc4
	s_lshr_b32 s3, s2, 6
	s_lshl_b32 s3, s3, 19
	s_and_b32 s13, s2, 63
	s_lshl_b32 s14, s13, 7
	s_add_u32 s3, s3, s14
	s_add_u32 s3, s3, 0x2200000
	s_movk_i32 s12, 0x2000
	s_branch .Lyc_sd4

; DI void yc_transpose_unit(KP p, int u, char* smem) {
;     ...
;   if (u < 2048) { b = u >> 9; cb = (u >> 6) & 7; tb = u & 63; rowlen = 4096;
;     src = (const u16*)(p->ws + OFF_YCT) + (size_t)(b * 512 + cb * 64) * 4096 + tb * 64;
;     dst = (u16*)(p->ws + OFF_YC) + (size_t)(b * 4096 + tb * 64) * 512 + cb * 64; }
;   else { const int uu = u - 2048; b = uu >> 5; cb = (uu >> 2) & 7; tb = uu & 3; rowlen = 256;
;     src = (const u16*)(p->ws + OFF_YCT) + (size_t)NB * 512 * 4096 + (size_t)(b * 512 + cb * 64) * 256 + tb * 64;
;     dst = (u16*)(p->ws + OFF_YC) + (size_t)(MLAT + b * 256 + tb * 64) * 512 + cb * 64; }
;   u16* tile = (u16*)smem;
;   const int r = tid >> 2, q = tid & 3;
;   __syncthreads();
;   {
;     const u32x4 v0 = *(const u32x4*)(src + (size_t)r * rowlen + q * 16);
;     const u32x4 v1 = *(const u32x4*)(src + (size_t)r * rowlen + q * 16 + 8);
;     unsigned* tp = (unsigned*)(tile + r * 66 + q * 16);
;     tp[0] = v0.x; tp[1] = v0.y; tp[2] = v0.z; tp[3] = v0.w; tp[4] = v1.x; tp[5] = v1.y; tp[6] = v1.z; tp[7] = v1.w;
;   }
;   __syncthreads();
;   {
;     unsigned o[8];
; #pragma unroll
;     for (int e = 0; e < 8; ++e)
;       o[e] = (unsigned)tile[(q * 16 + 2 * e) * 66 + r] | ((unsigned)tile[(q * 16 + 2 * e + 1) * 66 + r] << 16);
;     u16* d = dst + (size_t)r * 512 + q * 16;
;     *(u32x4*)d = u32x4{o[0], o[1], o[2], o[3]};
;     *(u32x4*)(d + 8) = u32x4{o[4], o[5], o[6], o[7]};
;   }
.Lyc_sd4:
	s_add_u32 s8, s4, s3
	s_addc_u32 s9, s5, 0
	v_mul_u32_u24_e32 v85, s12, v80
	v_add_u32_e32 v85, v85, v81
	s_add_i32 s10, s10, 1
	global_load_dwordx4 v[72:75], v85, s[8:9]
	global_load_dwordx4 v[76:79], v85, s[8:9] offset:16
.Lyc_loaded:
	s_mov_b32 s2, s26
	s_cmp_ge_i32 s2, s21
	s_cbranch_scc1 .Lyc_done
	s_add_i32 s2, s2, 0xfffff780
	s_cmpk_gt_u32 s2, 0x7ff
	s_cbranch_scc1 .Lyc_dc0
	s_lshr_b32 s3, s2, 9
	s_lshl_b32 s3, s3, 22
	s_and_b32 s13, s2, 63
	s_lshl_b32 s14, s13, 16
	s_add_u32 s3, s3, s14
	s_bfe_u32 s14, s2, 0x30006
	s_lshl_b32 s14, s14, 7
	s_add_u32 s3, s3, s14
	s_add_u32 s3, s3, 0x5a50000
	s_branch .Lyc_dd0
.Lyc_dc0:
	s_add_i32 s12, s2, 0xfffff800
	s_lshr_b32 s3, s12, 5
	s_lshl_b32 s3, s3, 18
	s_and_b32 s13, s12, 3
	s_lshl_b32 s14, s13, 16
	s_add_u32 s3, s3, s14
	s_bfe_u32 s14, s12, 0x30002
	s_lshl_b32 s14, s14, 7
	s_add_u32 s3, s3, s14
	s_add_u32 s3, s3, 0x6a50000
.Lyc_dd0:
	s_add_u32 s6, s4, s3
	s_addc_u32 s7, s5, 0
	s_cmp_eq_u32 s10, 5
	s_cbranch_scc1 .Lyc_w0_5
	s_cmp_eq_u32 s10, 4
	s_cbranch_scc1 .Lyc_w0_4
	s_cmp_eq_u32 s10, 3
	s_cbranch_scc1 .Lyc_w0_3
	s_cmp_eq_u32 s10, 2
	s_cbranch_scc1 .Lyc_w0_2
	s_waitcnt vmcnt(0)
	s_branch .Lyc_wd0
.Lyc_w0_5:
	s_waitcnt vmcnt(8)
	s_branch .Lyc_wd0
.Lyc_w0_4:
	s_waitcnt vmcnt(6)
	s_branch .Lyc_wd0
.Lyc_w0_3:
	s_waitcnt vmcnt(4)
	s_branch .Lyc_wd0
.Lyc_w0_2:
	s_waitcnt vmcnt(2)
.Lyc_wd0:
	s_barrier
	ds_write2_b32 v82, v40, v41 offset1:1
	ds_write2_b32 v82, v42, v43 offset0:2 offset1:3
	ds_write2_b32 v82, v44, v45 offset0:4 offset1:5
	ds_write2_b32 v82, v46, v47 offset0:6 offset1:7
	s_waitcnt lgkmcnt(0)
	s_barrier
	ds_read_u16 v86, v83
	ds_read_u16 v87, v83 offset:264
	ds_read_u16 v88, v83 offset:528
	ds_read_u16 v89, v83 offset:792
	ds_read_u16 v90, v83 offset:1056
	ds_read_u16 v91, v83 offset:1320
	ds_read_u16 v92, v83 offset:1584
	ds_read_u16 v93, v83 offset:1848
	ds_read_u16 v94, v83 offset:132
	ds_read_u16 v95, v83 offset:396
	ds_read_u16 v96, v83 offset:660
	ds_read_u16 v97, v83 offset:924
	ds_read_u16 v98, v83 offset:1188
	ds_read_u16 v99, v83 offset:1452
	ds_read_u16 v100, v83 offset:1716
	ds_read_u16 v101, v83 offset:1980
	s_waitcnt lgkmcnt(7)
	v_lshl_or_b32 v86, v94, 16, v86
	s_waitcnt lgkmcnt(6)
	v_lshl_or_b32 v87, v95, 16, v87
	s_waitcnt lgkmcnt(5)
	v_lshl_or_b32 v88, v96, 16, v88
	s_waitcnt lgkmcnt(4)
	v_lshl_or_b32 v89, v97, 16, v89
	s_waitcnt lgkmcnt(3)
	v_lshl_or_b32 v90, v98, 16, v90
	s_waitcnt lgkmcnt(2)
	v_lshl_or_b32 v91, v99, 16, v91
	s_waitcnt lgkmcnt(1)
	v_lshl_or_b32 v92, v100, 16, v92
	s_waitcnt lgkmcnt(0)
	v_lshl_or_b32 v93, v101, 16, v93
	global_store_dwordx4 v84, v[86:89], s[6:7]
	global_store_dwordx4 v84, v[90:93], s[6:7] offset:16
	s_mul_i32 s2, s61, 1
	s_add_i32 s2, s2, s26
	s_cmp_ge_i32 s2, s21
	s_cbranch_scc1 .Lyc_done
	s_add_i32 s2, s2, 0xfffff780
	s_cmpk_gt_u32 s2, 0x7ff
	s_cbranch_scc1 .Lyc_dc1
	s_lshr_b32 s3, s2, 9
	s_lshl_b32 s3, s3, 22
	s_and_b32 s13, s2, 63
	s_lshl_b32 s14, s13, 16
	s_add_u32 s3, s3, s14
	s_bfe_u32 s14, s2, 0x30006
	s_lshl_b32 s14, s14, 7
	s_add_u32 s3, s3, s14
	s_add_u32 s3, s3, 0x5a50000
	s_branch .Lyc_dd1

; DI void yc_transpose_unit(KP p, int u, char* smem) {
;     ...
;   if (u < 2048) { b = u >> 9; cb = (u >> 6) & 7; tb = u & 63; rowlen = 4096;
;     src = (const u16*)(p->ws + OFF_YCT) + (size_t)(b * 512 + cb * 64) * 4096 + tb * 64;
;     dst = (u16*)(p->ws + OFF_YC) + (size_t)(b * 4096 + tb * 64) * 512 + cb * 64; }
;     ...
;   __syncthreads();
;   {
;     const u32x4 v0 = *(const u32x4*)(src + (size_t)r * rowlen + q * 16);
;     const u32x4 v1 = *(const u32x4*)(src + (size_t)r * rowlen + q * 16 + 8);
;     unsigned* tp = (unsigned*)(tile + r * 66 + q * 16);
;     tp[0] = v0.x; tp[1] = v0.y; tp[2] = v0.z; tp[3] = v0.w; tp[4] = v1.x; tp[5] = v1.y; tp[6] = v1.z; tp[7] = v1.w;
;   }
;   __syncthreads();
;   {
;     unsigned o[8];
; #pragma unroll
;     for (int e = 0; e < 8; ++e)
;       o[e] = (unsigned)tile[(q * 16 + 2 * e) * 66 + r] | ((unsigned)tile[(q * 16 + 2 * e + 1) * 66 + r] << 16);
;     u16* d = dst + (size_t)r * 512 + q * 16;
;     *(u32x4*)d = u32x4{o[0], o[1], o[2], o[3]};
;     *(u32x4*)(d + 8) = u32x4{o[4], o[5], o[6], o[7]};
.Lyc_wd1:
	s_barrier
	ds_write2_b32 v82, v48, v49 offset1:1
	ds_write2_b32 v82, v50, v51 offset0:2 offset1:3
	ds_write2_b32 v82, v52, v53 offset0:4 offset1:5
	ds_write2_b32 v82, v54, v55 offset0:6 offset1:7
	s_waitcnt lgkmcnt(0)
	s_barrier
	ds_read_u16 v86, v83
	ds_read_u16 v87, v83 offset:264
	ds_read_u16 v88, v83 offset:528
	ds_read_u16 v89, v83 offset:792
	ds_read_u16 v90, v83 offset:1056
	ds_read_u16 v91, v83 offset:1320
	ds_read_u16 v92, v83 offset:1584
	ds_read_u16 v93, v83 offset:1848
	ds_read_u16 v94, v83 offset:132
	ds_read_u16 v95, v83 offset:396
	ds_read_u16 v96, v83 offset:660
	ds_read_u16 v97, v83 offset:924
	ds_read_u16 v98, v83 offset:1188
	ds_read_u16 v99, v83 offset:1452
	ds_read_u16 v100, v83 offset:1716
	ds_read_u16 v101, v83 offset:1980
	s_waitcnt lgkmcnt(7)
	v_lshl_or_b32 v86, v94, 16, v86
	s_waitcnt lgkmcnt(6)
	v_lshl_or_b32 v87, v95, 16, v87
	s_waitcnt lgkmcnt(5)
	v_lshl_or_b32 v88, v96, 16, v88
	s_waitcnt lgkmcnt(4)
	v_lshl_or_b32 v89, v97, 16, v89
	s_waitcnt lgkmcnt(3)
	v_lshl_or_b32 v90, v98, 16, v90
	s_waitcnt lgkmcnt(2)
	v_lshl_or_b32 v91, v99, 16, v91
	s_waitcnt lgkmcnt(1)
	v_lshl_or_b32 v92, v100, 16, v92
	s_waitcnt lgkmcnt(0)
	v_lshl_or_b32 v93, v101, 16, v93
	global_store_dwordx4 v84, v[86:89], s[6:7]
	global_store_dwordx4 v84, v[90:93], s[6:7] offset:16
	s_mul_i32 s2, s61, 2
	s_add_i32 s2, s2, s26
	s_cmp_ge_i32 s2, s21
	s_cbranch_scc1 .Lyc_done
	s_add_i32 s2, s2, 0xfffff780
	s_cmpk_gt_u32 s2, 0x7ff
	s_cbranch_scc1 .Lyc_dc2
	s_lshr_b32 s3, s2, 9
	s_lshl_b32 s3, s3, 22
	s_and_b32 s13, s2, 63
	s_lshl_b32 s14, s13, 16
	s_add_u32 s3, s3, s14
	s_bfe_u32 s14, s2, 0x30006
	s_lshl_b32 s14, s14, 7
	s_add_u32 s3, s3, s14
	s_add_u32 s3, s3, 0x5a50000
	s_branch .Lyc_dd2

; DI void yc_transpose_unit(KP p, int u, char* smem) {
;     ...
;   if (u < 2048) { b = u >> 9; cb = (u >> 6) & 7; tb = u & 63; rowlen = 4096;
;     src = (const u16*)(p->ws + OFF_YCT) + (size_t)(b * 512 + cb * 64) * 4096 + tb * 64;
;     dst = (u16*)(p->ws + OFF_YC) + (size_t)(b * 4096 + tb * 64) * 512 + cb * 64; }
;     ...
;   __syncthreads();
;   {
;     const u32x4 v0 = *(const u32x4*)(src + (size_t)r * rowlen + q * 16);
;     const u32x4 v1 = *(const u32x4*)(src + (size_t)r * rowlen + q * 16 + 8);
;     unsigned* tp = (unsigned*)(tile + r * 66 + q * 16);
;     tp[0] = v0.x; tp[1] = v0.y; tp[2] = v0.z; tp[3] = v0.w; tp[4] = v1.x; tp[5] = v1.y; tp[6] = v1.z; tp[7] = v1.w;
;   }
;   __syncthreads();
;   {
;     unsigned o[8];
; #pragma unroll
;     for (int e = 0; e < 8; ++e)
;       o[e] = (unsigned)tile[(q * 16 + 2 * e) * 66 + r] | ((unsigned)tile[(q * 16 + 2 * e + 1) * 66 + r] << 16);
;     u16* d = dst + (size_t)r * 512 + q * 16;
;     *(u32x4*)d = u32x4{o[0], o[1], o[2], o[3]};
;     *(u32x4*)(d + 8) = u32x4{o[4], o[5], o[6], o[7]};
.Lyc_wd2:
	s_barrier
	ds_write2_b32 v82, v56, v57 offset1:1
	ds_write2_b32 v82, v58, v59 offset0:2 offset1:3
	ds_write2_b32 v82, v60, v61 offset0:4 offset1:5
	ds_write2_b32 v82, v62, v63 offset0:6 offset1:7
	s_waitcnt lgkmcnt(0)
	s_barrier
	ds_read_u16 v86, v83
	ds_read_u16 v87, v83 offset:264
	ds_read_u16 v88, v83 offset:528
	ds_read_u16 v89, v83 offset:792
	ds_read_u16 v90, v83 offset:1056
	ds_read_u16 v91, v83 offset:1320
	ds_read_u16 v92, v83 offset:1584
	ds_read_u16 v93, v83 offset:1848
	ds_read_u16 v94, v83 offset:132
	ds_read_u16 v95, v83 offset:396
	ds_read_u16 v96, v83 offset:660
	ds_read_u16 v97, v83 offset:924
	ds_read_u16 v98, v83 offset:1188
	ds_read_u16 v99, v83 offset:1452
	ds_read_u16 v100, v83 offset:1716
	ds_read_u16 v101, v83 offset:1980
	s_waitcnt lgkmcnt(7)
	v_lshl_or_b32 v86, v94, 16, v86
	s_waitcnt lgkmcnt(6)
	v_lshl_or_b32 v87, v95, 16, v87
	s_waitcnt lgkmcnt(5)
	v_lshl_or_b32 v88, v96, 16, v88
	s_waitcnt lgkmcnt(4)
	v_lshl_or_b32 v89, v97, 16, v89
	s_waitcnt lgkmcnt(3)
	v_lshl_or_b32 v90, v98, 16, v90
	s_waitcnt lgkmcnt(2)
	v_lshl_or_b32 v91, v99, 16, v91
	s_waitcnt lgkmcnt(1)
	v_lshl_or_b32 v92, v100, 16, v92
	s_waitcnt lgkmcnt(0)
	v_lshl_or_b32 v93, v101, 16, v93
	global_store_dwordx4 v84, v[86:89], s[6:7]
	global_store_dwordx4 v84, v[90:93], s[6:7] offset:16
	s_mul_i32 s2, s61, 3
	s_add_i32 s2, s2, s26
	s_cmp_ge_i32 s2, s21
	s_cbranch_scc1 .Lyc_done
	s_add_i32 s2, s2, 0xfffff780
	s_cmpk_gt_u32 s2, 0x7ff
	s_cbranch_scc1 .Lyc_dc3
	s_lshr_b32 s3, s2, 9
	s_lshl_b32 s3, s3, 22
	s_and_b32 s13, s2, 63
	s_lshl_b32 s14, s13, 16
	s_add_u32 s3, s3, s14
	s_bfe_u32 s14, s2, 0x30006
	s_lshl_b32 s14, s14, 7
	s_add_u32 s3, s3, s14
	s_add_u32 s3, s3, 0x5a50000
	s_branch .Lyc_dd3

; DI void yc_transpose_unit(KP p, int u, char* smem) {
;     ...
;   if (u < 2048) { b = u >> 9; cb = (u >> 6) & 7; tb = u & 63; rowlen = 4096;
;     src = (const u16*)(p->ws + OFF_YCT) + (size_t)(b * 512 + cb * 64) * 4096 + tb * 64;
;     dst = (u16*)(p->ws + OFF_YC) + (size_t)(b * 4096 + tb * 64) * 512 + cb * 64; }
;     ...
;   __syncthreads();
;   {
;     const u32x4 v0 = *(const u32x4*)(src + (size_t)r * rowlen + q * 16);
;     const u32x4 v1 = *(const u32x4*)(src + (size_t)r * rowlen + q * 16 + 8);
;     unsigned* tp = (unsigned*)(tile + r * 66 + q * 16);
;     tp[0] = v0.x; tp[1] = v0.y; tp[2] = v0.z; tp[3] = v0.w; tp[4] = v1.x; tp[5] = v1.y; tp[6] = v1.z; tp[7] = v1.w;
;   }
;   __syncthreads();
;   {
;     unsigned o[8];
; #pragma unroll
;     for (int e = 0; e < 8; ++e)
;       o[e] = (unsigned)tile[(q * 16 + 2 * e) * 66 + r] | ((unsigned)tile[(q * 16 + 2 * e + 1) * 66 + r] << 16);
;     u16* d = dst + (size_t)r * 512 + q * 16;
;     *(u32x4*)d = u32x4{o[0], o[1], o[2], o[3]};
;     *(u32x4*)(d + 8) = u32x4{o[4], o[5], o[6], o[7]};
.Lyc_wd3:
	s_barrier
	ds_write2_b32 v82, v64, v65 offset1:1
	ds_write2_b32 v82, v66, v67 offset0:2 offset1:3
	ds_write2_b32 v82, v68, v69 offset0:4 offset1:5
	ds_write2_b32 v82, v70, v71 offset0:6 offset1:7
	s_waitcnt lgkmcnt(0)
	s_barrier
	ds_read_u16 v86, v83
	ds_read_u16 v87, v83 offset:264
	ds_read_u16 v88, v83 offset:528
	ds_read_u16 v89, v83 offset:792
	ds_read_u16 v90, v83 offset:1056
	ds_read_u16 v91, v83 offset:1320
	ds_read_u16 v92, v83 offset:1584
	ds_read_u16 v93, v83 offset:1848
	ds_read_u16 v94, v83 offset:132
	ds_read_u16 v95, v83 offset:396
	ds_read_u16 v96, v83 offset:660
	ds_read_u16 v97, v83 offset:924
	ds_read_u16 v98, v83 offset:1188
	ds_read_u16 v99, v83 offset:1452
	ds_read_u16 v100, v83 offset:1716
	ds_read_u16 v101, v83 offset:1980
	s_waitcnt lgkmcnt(7)
	v_lshl_or_b32 v86, v94, 16, v86
	s_waitcnt lgkmcnt(6)
	v_lshl_or_b32 v87, v95, 16, v87
	s_waitcnt lgkmcnt(5)
	v_lshl_or_b32 v88, v96, 16, v88
	s_waitcnt lgkmcnt(4)
	v_lshl_or_b32 v89, v97, 16, v89
	s_waitcnt lgkmcnt(3)
	v_lshl_or_b32 v90, v98, 16, v90
	s_waitcnt lgkmcnt(2)
	v_lshl_or_b32 v91, v99, 16, v91
	s_waitcnt lgkmcnt(1)
	v_lshl_or_b32 v92, v100, 16, v92
	s_waitcnt lgkmcnt(0)
	v_lshl_or_b32 v93, v101, 16, v93
	global_store_dwordx4 v84, v[86:89], s[6:7]
	global_store_dwordx4 v84, v[90:93], s[6:7] offset:16
	s_mul_i32 s2, s61, 4
	s_add_i32 s2, s2, s26
	s_cmp_ge_i32 s2, s21
	s_cbranch_scc1 .Lyc_done
	s_add_i32 s2, s2, 0xfffff780
	s_cmpk_gt_u32 s2, 0x7ff
	s_cbranch_scc1 .Lyc_dc4
	s_lshr_b32 s3, s2, 9
	s_lshl_b32 s3, s3, 22
	s_and_b32 s13, s2, 63
	s_lshl_b32 s14, s13, 16
	s_add_u32 s3, s3, s14
	s_bfe_u32 s14, s2, 0x30006
	s_lshl_b32 s14, s14, 7
	s_add_u32 s3, s3, s14
	s_add_u32 s3, s3, 0x5a50000
	s_branch .Lyc_dd4

; static __device__ __forceinline__ KP lp(KP q) { asm volatile("" : "+s"(q)); return q; }
; DI void yc_transpose_unit(KP p, int u, char* smem) {
;     ...
;   __syncthreads();
;   {
;     const u32x4 v0 = *(const u32x4*)(src + (size_t)r * rowlen + q * 16);
;     const u32x4 v1 = *(const u32x4*)(src + (size_t)r * rowlen + q * 16 + 8);
;     unsigned* tp = (unsigned*)(tile + r * 66 + q * 16);
;     tp[0] = v0.x; tp[1] = v0.y; tp[2] = v0.z; tp[3] = v0.w; tp[4] = v1.x; tp[5] = v1.y; tp[6] = v1.z; tp[7] = v1.w;
;   }
;   __syncthreads();
;   {
;     unsigned o[8];
; #pragma unroll
;     for (int e = 0; e < 8; ++e)
;       o[e] = (unsigned)tile[(q * 16 + 2 * e) * 66 + r] | ((unsigned)tile[(q * 16 + 2 * e + 1) * 66 + r] << 16);
;     u16* d = dst + (size_t)r * 512 + q * 16;
;     *(u32x4*)d = u32x4{o[0], o[1], o[2], o[3]};
;     *(u32x4*)(d + 8) = u32x4{o[4], o[5], o[6], o[7]};
; __global__ void __launch_bounds__(256, 2) trunk_megakernel(Params pk) {
;     ...
;       for (int u = B; u < 2176 + (l ? 2048 : 2176); u += G) {
;         if (u < 2176) { if (l == 0 || ((u % 544) >> 3) >= 4) lru_unit(lp(p), l, u, 3, smem, rep + 1 < REP_L3); }
;         else yc_transpose_unit(lp(p), u - 2176, smem);
.Lyc_wd4:
	s_barrier
	ds_write2_b32 v82, v72, v73 offset1:1
	ds_write2_b32 v82, v74, v75 offset0:2 offset1:3
	ds_write2_b32 v82, v76, v77 offset0:4 offset1:5
	ds_write2_b32 v82, v78, v79 offset0:6 offset1:7
	s_waitcnt lgkmcnt(0)
	s_barrier
	ds_read_u16 v86, v83
	ds_read_u16 v87, v83 offset:264
	ds_read_u16 v88, v83 offset:528
	ds_read_u16 v89, v83 offset:792
	ds_read_u16 v90, v83 offset:1056
	ds_read_u16 v91, v83 offset:1320
	ds_read_u16 v92, v83 offset:1584
	ds_read_u16 v93, v83 offset:1848
	ds_read_u16 v94, v83 offset:132
	ds_read_u16 v95, v83 offset:396
	ds_read_u16 v96, v83 offset:660
	ds_read_u16 v97, v83 offset:924
	ds_read_u16 v98, v83 offset:1188
	ds_read_u16 v99, v83 offset:1452
	ds_read_u16 v100, v83 offset:1716
	ds_read_u16 v101, v83 offset:1980
	s_waitcnt lgkmcnt(7)
	v_lshl_or_b32 v86, v94, 16, v86
	s_waitcnt lgkmcnt(6)
	v_lshl_or_b32 v87, v95, 16, v87
	s_waitcnt lgkmcnt(5)
	v_lshl_or_b32 v88, v96, 16, v88
	s_waitcnt lgkmcnt(4)
	v_lshl_or_b32 v89, v97, 16, v89
	s_waitcnt lgkmcnt(3)
	v_lshl_or_b32 v90, v98, 16, v90
	s_waitcnt lgkmcnt(2)
	v_lshl_or_b32 v91, v99, 16, v91
	s_waitcnt lgkmcnt(1)
	v_lshl_or_b32 v92, v100, 16, v92
	s_waitcnt lgkmcnt(0)
	v_lshl_or_b32 v93, v101, 16, v93
	global_store_dwordx4 v84, v[86:89], s[6:7]
	global_store_dwordx4 v84, v[90:93], s[6:7] offset:16
.Lyc_done:
	s_add_i32 s10, s10, -1
	s_mul_i32 s10, s10, s61
	s_add_i32 s26, s26, s10
	s_branch .LBB0_1155
